# v97 + conv second-tile row/halo loads prefetched during first tile (software prefetch of next tile's 38 loads)
# baseline (speedup 1.0000x reference)
; #define LAS __attribute__((address_space(3)))
; __global__ void __launch_bounds__(NWAVES * 64, 2) mk_fwd(Args args) {
;     ...
;             const int cp = tid & 255, th = tid >> 8;
;             f32x2 w[31];
; #pragma unroll
;             for (int j = 0; j < 31; ++j) w[j] = *(const f32x2*)(conv_w + j * 512 + 2 * cp);
;             const f32x2 cb = *(const f32x2*)(conv_b + 2 * cp);
;             LAS float* yt = (LAS float*)lds;
;             f32x4 lg0 = *(const f32x4*)(ln_g + 4 * lane), lg1 = *(const f32x4*)(ln_g + 256 + 4 * lane), lb0 = *(const f32x4*)(ln_b + 4 * lane), lb1 = *(const f32x4*)(ln_b + 256 + 4 * lane);
;     ...
;             for (int repc = 0; repc < REPC; ++repc)
;             for (int kt = 0, tile = (G == 256) ? 64 * (vcu >> 5) + (vcu & 31) : vcu; tile < T / 64; ++kt, tile = (G == 256) ? ((kt < 2) ? 64 * (vcu >> 5) + 32 * kt + (vcu & 31) : T) : tile + G) {
.LBB0_352:
	s_lshl_b32 s4, s73, 1
	s_andn2_b32 s4, s4, 63
	s_and_b32 s5, s73, 31
	s_or_b32 s4, s4, s5
	s_and_b64 s[6:7], s[50:51], exec
	s_cselect_b32 s6, s4, s73
	s_cmpk_lt_i32 s6, 0x200
	s_cbranch_scc0 .LBB0_361
	v_lshlrev_b32_e32 v0, 1, v200
	v_and_b32_e32 v20, 0x1fe, v0
	v_mov_b32_e32 v80, 0
	v_lshlrev_b32_e32 v0, 2, v20
	v_mov_b32_e32 v1, v80
	v_lshl_add_u64 v[2:3], s[18:19], 0, v[0:1]
	v_add_co_u32_e32 v4, vcc, 0x1000, v2
	v_lshl_add_u64 v[0:1], s[16:17], 0, v[0:1]
	s_nop 0
	v_addc_co_u32_e32 v5, vcc, 0, v3, vcc
	flat_load_dwordx2 v[82:83], v[2:3]
	flat_load_dwordx2 v[84:85], v[2:3] offset:2048
	flat_load_dwordx2 v[86:87], v[4:5]
	flat_load_dwordx2 v[88:89], v[4:5] offset:2048
	v_add_co_u32_e32 v4, vcc, 0x2000, v2
	v_mov_b32_e32 v17, v80
	s_nop 0
	v_addc_co_u32_e32 v5, vcc, 0, v3, vcc
	v_add_co_u32_e32 v6, vcc, 0x3000, v2
	s_ashr_i32 s5, s72, 6
	s_nop 0
	v_addc_co_u32_e32 v7, vcc, 0, v3, vcc
	flat_load_dwordx2 v[90:91], v[4:5]
	flat_load_dwordx2 v[92:93], v[4:5] offset:2048
	flat_load_dwordx2 v[94:95], v[6:7]
	flat_load_dwordx2 v[96:97], v[6:7] offset:2048
	v_add_co_u32_e32 v4, vcc, 0x4000, v2
	s_movk_i32 s7, 0x1000
	s_nop 0
	v_addc_co_u32_e32 v5, vcc, 0, v3, vcc
	v_add_co_u32_e32 v6, vcc, 0x5000, v2
	s_movk_i32 s8, 0x2000
	s_nop 0
	v_addc_co_u32_e32 v7, vcc, 0, v3, vcc
	flat_load_dwordx2 v[98:99], v[4:5]
	s_nop 0
	flat_load_dwordx2 v[100:101], v[4:5] offset:2048
	flat_load_dwordx2 v[102:103], v[6:7]
	flat_load_dwordx2 v[104:105], v[6:7] offset:2048
	v_add_co_u32_e32 v4, vcc, 0x6000, v2
	s_movk_i32 s9, 0x3000
	s_nop 0
	v_addc_co_u32_e32 v5, vcc, 0, v3, vcc
	v_add_co_u32_e32 v6, vcc, 0x7000, v2
	v_mov_b32_e32 v176, 0x358637bd
	s_nop 0
	v_addc_co_u32_e32 v7, vcc, 0, v3, vcc
	flat_load_dwordx2 v[106:107], v[4:5]
	flat_load_dwordx2 v[108:109], v[4:5] offset:2048
	flat_load_dwordx2 v[110:111], v[6:7]
	flat_load_dwordx2 v[112:113], v[6:7] offset:2048
	v_add_co_u32_e32 v4, vcc, 0x8000, v2
	v_mov_b32_e32 v177, 0x260
	s_nop 0
	v_addc_co_u32_e32 v5, vcc, 0, v3, vcc
	v_add_co_u32_e32 v6, vcc, 0x9000, v2
	s_nop 1
	v_addc_co_u32_e32 v7, vcc, 0, v3, vcc
	flat_load_dwordx2 v[114:115], v[4:5]
	flat_load_dwordx2 v[116:117], v[4:5] offset:2048
	flat_load_dwordx2 v[118:119], v[6:7]
	flat_load_dwordx2 v[120:121], v[6:7] offset:2048
	v_add_co_u32_e32 v4, vcc, 0xa000, v2
	s_nop 1
	v_addc_co_u32_e32 v5, vcc, 0, v3, vcc
	v_add_co_u32_e32 v6, vcc, 0xb000, v2
	s_nop 1
	v_addc_co_u32_e32 v7, vcc, 0, v3, vcc
	flat_load_dwordx2 v[122:123], v[4:5]
	flat_load_dwordx2 v[124:125], v[4:5] offset:2048
	flat_load_dwordx2 v[126:127], v[6:7]
	flat_load_dwordx2 v[128:129], v[6:7] offset:2048
	v_add_co_u32_e32 v4, vcc, 0xc000, v2
	s_nop 1
	v_addc_co_u32_e32 v5, vcc, 0, v3, vcc
	v_add_co_u32_e32 v6, vcc, 0xd000, v2
	s_nop 1
	v_addc_co_u32_e32 v7, vcc, 0, v3, vcc
	flat_load_dwordx2 v[130:131], v[4:5]
	flat_load_dwordx2 v[132:133], v[4:5] offset:2048
	flat_load_dwordx2 v[134:135], v[6:7]
	flat_load_dwordx2 v[136:137], v[6:7] offset:2048
	v_add_co_u32_e32 v4, vcc, 0xe000, v2
	s_nop 1
	v_addc_co_u32_e32 v5, vcc, 0, v3, vcc
	v_add_co_u32_e32 v2, vcc, 0xf000, v2
	s_nop 1
	v_addc_co_u32_e32 v3, vcc, 0, v3, vcc
	flat_load_dwordx2 v[138:139], v[4:5]
	flat_load_dwordx2 v[140:141], v[4:5] offset:2048
	flat_load_dwordx2 v[142:143], v[2:3]
	flat_load_dwordx2 v[144:145], v[0:1]
	v_lshlrev_b32_e32 v0, 2, v200
	v_and_b32_e32 v21, 0xfc, v0
	v_lshlrev_b32_e32 v16, 2, v21
	v_lshl_add_u64 v[8:9], s[12:13], 0, v[16:17]
	v_lshl_add_u64 v[18:19], s[14:15], 0, v[16:17]
	flat_load_dwordx4 v[0:3], v[8:9]
	flat_load_dwordx4 v[4:7], v[8:9] offset:1024
	s_nop 0
	flat_load_dwordx4 v[8:11], v[18:19]
	flat_load_dwordx4 v[12:15], v[18:19] offset:1024
	v_lshlrev_b32_e32 v18, 1, v20
	v_mov_b32_e32 v19, v80
	v_lshl_add_u64 v[18:19], s[2:3], 0, v[18:19]
	s_mov_b64 s[14:15], 0x8000000
	v_mbcnt_lo_u32_b32 v17, -1, 0
	v_lshl_add_u64 v[146:147], v[18:19], 0, s[14:15]
	s_or_b32 s15, s4, 32
	s_lshl_b32 s4, s5, 14
	v_mbcnt_hi_u32_b32 v17, -1, v17
	s_add_i32 s4, s4, 0
	v_and_b32_e32 v19, 64, v17
	v_add_u32_e32 v19, 64, v19
	v_add_u32_e32 v168, s4, v16
	v_xor_b32_e32 v16, 1, v17
	v_cmp_lt_i32_e32 vcc, v16, v19
	s_lshl_b32 s14, s5, 3
	s_mov_b64 s[4:5], 0x14000000
	v_cndmask_b32_e32 v16, v17, v16, vcc
	v_lshlrev_b32_e32 v169, 2, v16
	v_xor_b32_e32 v16, 2, v17
	v_cmp_lt_i32_e32 vcc, v16, v19
	v_ashrrev_i32_e32 v18, 3, v200
	v_and_b32_e32 v166, 0xffffffe0, v18
	v_cndmask_b32_e32 v16, v17, v16, vcc
	v_lshlrev_b32_e32 v170, 2, v16
	v_xor_b32_e32 v16, 4, v17
	v_cmp_lt_i32_e32 vcc, v16, v19
	s_mov_b32 s13, 0
	s_movk_i32 s12, 0x5000
	v_cndmask_b32_e32 v16, v17, v16, vcc
	v_lshlrev_b32_e32 v171, 2, v16
	v_xor_b32_e32 v16, 8, v17
	v_cmp_lt_i32_e32 vcc, v16, v19
	v_sub_u32_e32 v167, 0, v166
	s_nop 0
	v_cndmask_b32_e32 v16, v17, v16, vcc
	v_lshlrev_b32_e32 v172, 2, v16
	v_xor_b32_e32 v16, 16, v17
	v_cmp_lt_i32_e32 vcc, v16, v19
	s_nop 1
	v_cndmask_b32_e32 v16, v17, v16, vcc
	v_lshlrev_b32_e32 v173, 2, v16
	v_xor_b32_e32 v16, 32, v17
	v_cmp_lt_i32_e32 vcc, v16, v19
	s_nop 1
	v_cndmask_b32_e32 v16, v17, v16, vcc
	v_lshlrev_b32_e32 v174, 2, v16
	v_lshlrev_b32_e32 v16, 1, v21
	v_mov_b32_e32 v17, v80
	v_lshl_add_u64 v[16:17], s[10:11], 0, v[16:17]
	v_lshl_add_u64 v[148:149], v[16:17], 0, s[4:5]
	v_mov_b32_e32 v16, 2
	v_lshlrev_b32_sdwa v16, v16, v200 dst_sel:DWORD dst_unused:UNUSED_PAD src0_sel:DWORD src1_sel:BYTE_0
	v_mov_b32_e32 v17, v80
	v_lshl_add_u64 v[150:151], s[2:3], 0, v[16:17]
	v_mov_b32_e32 v17, 3
	v_lshlrev_b32_e32 v16, 11, v18
	v_lshlrev_b32_sdwa v17, v17, v200 dst_sel:DWORD dst_unused:UNUSED_PAD src0_sel:DWORD src1_sel:BYTE_0
	s_mov_b32 s2, 0xffff0000
	v_and_or_b32 v16, v16, s2, v17
	v_add_u32_e32 v175, 0, v16
	s_movk_i32 s10, 0x1400
	s_mov_b32 s11, 0xf800000
	s_mov_b32 s96, 0
	s_branch .LBB0_355

; #define GLU2(uu) ((f32x2){bflo(uu), bfhi(uu)})
; __global__ void __launch_bounds__(NWAVES * 64, 2) mk_fwd(Args args) {
;     ...
;             for (int kt = 0, tile = (G == 256) ? 64 * (vcu >> 5) + (vcu & 31) : vcu; tile < T / 64; ++kt, tile = (G == 256) ? ((kt < 2) ? 64 * (vcu >> 5) + 32 * kt + (vcu & 31) : T) : tile + G) {
;                 const int R0 = tile * 64, tl0 = R0 % SEQ;
;                 const bf16* zb = Z + (size_t)(R0 + 32 * th) * ZP + 2 * cp;
;                 f32x2 win[38]; unsigned ru[8];
; #pragma unroll
;                 for (int i = 0; i < 38; ++i) win[i] = (f32x2){0.f, 0.f};
;                 if (tl0 + 32 * th > 0) {
; #pragma unroll
;                     for (int i = 0; i < 30; ++i) { const bf16* zr = zb + (long)(i - 30) * ZP; const unsigned uu = *(const unsigned*)zr; win[8 + i] = GLU2(uu); } }
; #pragma unroll
;                 for (int i = 0; i < 8; ++i) { const bf16* zr = zb + (long)i * ZP; ru[i] = *(const unsigned*)zr; }
.LBB0_355:
	s_bfe_i32 s2, s6, 0x10019
	s_lshl_b32 s4, s6, 6
	s_lshr_b32 s2, s2, 21
	s_add_i32 s2, s4, s2
	s_and_b32 s2, s2, 0xfffff800
	v_add_u32_e32 v76, s4, v166
	s_sub_i32 s5, s4, s2
	v_mov_b32_e32 v81, v80
	v_mad_i64_i32 v[60:61], s[2:3], v76, s10, v[146:147]
	v_cmp_gt_i32_e32 vcc, s5, v167
	v_mov_b64_e32 v[64:65], v[80:81]
	v_mov_b64_e32 v[62:63], v[80:81]
	v_mov_b64_e32 v[56:57], v[80:81]
	v_mov_b64_e32 v[54:55], v[80:81]
	v_mov_b64_e32 v[52:53], v[80:81]
	v_mov_b64_e32 v[50:51], v[80:81]
	v_mov_b64_e32 v[38:39], v[80:81]
	v_mov_b64_e32 v[36:37], v[80:81]
	v_mov_b64_e32 v[34:35], v[80:81]
	v_mov_b64_e32 v[32:33], v[80:81]
	v_mov_b64_e32 v[30:31], v[80:81]
	v_mov_b64_e32 v[28:29], v[80:81]
	v_mov_b64_e32 v[26:27], v[80:81]
	v_mov_b64_e32 v[24:25], v[80:81]
	v_mov_b64_e32 v[22:23], v[80:81]
	v_mov_b64_e32 v[20:21], v[80:81]
	v_mov_b64_e32 v[18:19], v[80:81]
	v_mov_b64_e32 v[16:17], v[80:81]
	v_mov_b64_e32 v[46:47], v[80:81]
	v_mov_b64_e32 v[58:59], v[80:81]
	v_mov_b64_e32 v[70:71], v[80:81]
	v_mov_b64_e32 v[72:73], v[80:81]
	v_mov_b64_e32 v[74:75], v[80:81]
	v_mov_b64_e32 v[78:79], v[80:81]
	v_mov_b32_e32 v66, 0
	v_mov_b32_e32 v67, 0
	v_mov_b32_e32 v68, 0
	v_mov_b32_e32 v69, 0
	v_mov_b32_e32 v40, 0
	v_mov_b32_e32 v41, 0
	v_mov_b32_e32 v42, 0
	v_mov_b32_e32 v43, 0
	v_mov_b32_e32 v44, 0
	v_mov_b32_e32 v45, 0
	v_mov_b32_e32 v48, 0
	v_mov_b32_e32 v49, 0
	s_mov_b32 s92, 0x1400
	s_mov_b32 s93, 0
	s_mov_b32 s94, 0xfffda800
	s_mov_b32 s95, -1
	s_cmp_lg_u32 s96, 0
	s_cbranch_scc1 .Lcv_ru_done
	v_mov_b64_e32 v[242:243], v[60:61]
	global_load_dword v232, v[242:243], off
	v_lshl_add_u64 v[242:243], v[242:243], 0, s[92:93]
	global_load_dword v233, v[242:243], off
	v_lshl_add_u64 v[242:243], v[242:243], 0, s[92:93]
	global_load_dword v234, v[242:243], off
	v_lshl_add_u64 v[242:243], v[242:243], 0, s[92:93]
	global_load_dword v235, v[242:243], off
	v_lshl_add_u64 v[242:243], v[242:243], 0, s[92:93]
	global_load_dword v236, v[242:243], off
	v_lshl_add_u64 v[242:243], v[242:243], 0, s[92:93]
	global_load_dword v237, v[242:243], off
	v_lshl_add_u64 v[242:243], v[242:243], 0, s[92:93]
	global_load_dword v238, v[242:243], off
	v_lshl_add_u64 v[242:243], v[242:243], 0, s[92:93]
	global_load_dword v239, v[242:243], off
.Lcv_ru_done:
	s_and_saveexec_b64 s[2:3], vcc
	s_cbranch_execz .LBB0_357
	s_cmp_lg_u32 s96, 0
	s_cbranch_scc1 .Lcv_halo_done
	v_lshl_add_u64 v[240:241], v[60:61], 0, s[94:95]
	global_load_dword v201, v[240:241], off
	v_lshl_add_u64 v[240:241], v[240:241], 0, s[92:93]
	global_load_dword v202, v[240:241], off
	v_lshl_add_u64 v[240:241], v[240:241], 0, s[92:93]
	global_load_dword v203, v[240:241], off
	v_lshl_add_u64 v[240:241], v[240:241], 0, s[92:93]
	global_load_dword v204, v[240:241], off
	v_lshl_add_u64 v[240:241], v[240:241], 0, s[92:93]
	global_load_dword v205, v[240:241], off
	v_lshl_add_u64 v[240:241], v[240:241], 0, s[92:93]
	global_load_dword v206, v[240:241], off
	v_lshl_add_u64 v[240:241], v[240:241], 0, s[92:93]
	global_load_dword v207, v[240:241], off
	v_lshl_add_u64 v[240:241], v[240:241], 0, s[92:93]
	global_load_dword v208, v[240:241], off
	v_lshl_add_u64 v[240:241], v[240:241], 0, s[92:93]
	global_load_dword v209, v[240:241], off
	v_lshl_add_u64 v[240:241], v[240:241], 0, s[92:93]
	global_load_dword v210, v[240:241], off
	v_lshl_add_u64 v[240:241], v[240:241], 0, s[92:93]
	global_load_dword v211, v[240:241], off
	v_lshl_add_u64 v[240:241], v[240:241], 0, s[92:93]
	global_load_dword v212, v[240:241], off
	v_lshl_add_u64 v[240:241], v[240:241], 0, s[92:93]
	global_load_dword v213, v[240:241], off
	v_lshl_add_u64 v[240:241], v[240:241], 0, s[92:93]
	global_load_dword v214, v[240:241], off
	v_lshl_add_u64 v[240:241], v[240:241], 0, s[92:93]
	global_load_dword v215, v[240:241], off
	v_lshl_add_u64 v[240:241], v[240:241], 0, s[92:93]
	global_load_dword v216, v[240:241], off
	v_lshl_add_u64 v[240:241], v[240:241], 0, s[92:93]
	global_load_dword v217, v[240:241], off
	v_lshl_add_u64 v[240:241], v[240:241], 0, s[92:93]
	global_load_dword v218, v[240:241], off
	v_lshl_add_u64 v[240:241], v[240:241], 0, s[92:93]
	global_load_dword v219, v[240:241], off
	v_lshl_add_u64 v[240:241], v[240:241], 0, s[92:93]
	global_load_dword v221, v[240:241], off
	v_lshl_add_u64 v[240:241], v[240:241], 0, s[92:93]
	global_load_dword v222, v[240:241], off
	v_lshl_add_u64 v[240:241], v[240:241], 0, s[92:93]
	global_load_dword v223, v[240:241], off
	v_lshl_add_u64 v[240:241], v[240:241], 0, s[92:93]
	global_load_dword v224, v[240:241], off
	v_lshl_add_u64 v[240:241], v[240:241], 0, s[92:93]
	global_load_dword v225, v[240:241], off
	v_lshl_add_u64 v[240:241], v[240:241], 0, s[92:93]
	global_load_dword v226, v[240:241], off
	v_lshl_add_u64 v[240:241], v[240:241], 0, s[92:93]
	global_load_dword v227, v[240:241], off
	v_lshl_add_u64 v[240:241], v[240:241], 0, s[92:93]
	global_load_dword v228, v[240:241], off
	v_lshl_add_u64 v[240:241], v[240:241], 0, s[92:93]
	global_load_dword v229, v[240:241], off
	v_lshl_add_u64 v[240:241], v[240:241], 0, s[92:93]
	global_load_dword v230, v[240:241], off
	v_lshl_add_u64 v[240:241], v[240:241], 0, s[92:93]
	global_load_dword v231, v[240:241], off
; #define GLU2(uu) ((f32x2){bflo(uu), bfhi(uu)})
; __global__ void __launch_bounds__(NWAVES * 64, 2) mk_fwd(Args args) {
;     ...
;                 if (tl0 + 32 * th > 0) {
; #pragma unroll
;                     for (int i = 0; i < 30; ++i) { const bf16* zr = zb + (long)(i - 30) * ZP; const unsigned uu = *(const unsigned*)zr; win[8 + i] = GLU2(uu); } }
; #pragma unroll
;                 for (int i = 0; i < 8; ++i) { const bf16* zr = zb + (long)i * ZP; ru[i] = *(const unsigned*)zr; }
; #pragma unroll 1
;                 for (int blk = 0; blk < 4; ++blk) {
;                     const int tb = 32 * th + 8 * blk;
; #pragma unroll
;                     for (int i = 0; i < 30; ++i) win[i] = win[i + 8];
; #pragma unroll
;                     for (int i = 0; i < 8; ++i) win[30 + i] = GLU2(ru[i]);
.Lcv_halo_done:
	s_waitcnt vmcnt(0)
	v_mov_b32_e32 v32, v201
	v_mov_b32_e32 v33, v202
	v_mov_b32_e32 v34, v203
	v_mov_b32_e32 v35, v204
	v_mov_b32_e32 v36, v205
	v_mov_b32_e32 v37, v206
	v_mov_b32_e32 v38, v207
	v_mov_b32_e32 v39, v208
	s_waitcnt vmcnt(0) lgkmcnt(0)
	v_lshlrev_b32_e32 v78, 16, v32
	v_and_b32_e32 v79, 0xffff0000, v32
	s_nop 0
	v_lshlrev_b32_e32 v74, 16, v33
	s_nop 0
	v_and_b32_e32 v75, 0xffff0000, v33
	s_nop 0
	v_lshlrev_b32_e32 v72, 16, v34
	s_nop 0
	v_and_b32_e32 v73, 0xffff0000, v34
	s_nop 0
	v_lshlrev_b32_e32 v70, 16, v35
	s_nop 0
	v_and_b32_e32 v71, 0xffff0000, v35
	s_nop 0
	v_mov_b32_e32 v40, v209
	v_mov_b32_e32 v41, v210
	v_mov_b32_e32 v42, v211
	v_mov_b32_e32 v43, v212
	v_mov_b32_e32 v50, v213
	v_mov_b32_e32 v51, v214
	v_mov_b32_e32 v52, v215
	v_mov_b32_e32 v53, v216
	v_lshlrev_b32_e32 v58, 16, v36
	s_nop 0
	v_and_b32_e32 v59, 0xffff0000, v36
	s_nop 0
	v_lshlrev_b32_e32 v46, 16, v37
	s_nop 0
	v_and_b32_e32 v47, 0xffff0000, v37
	s_nop 0
	v_lshlrev_b32_e32 v48, 16, v38
	s_nop 0
	v_and_b32_e32 v49, 0xffff0000, v38
	s_nop 0
	v_lshlrev_b32_e32 v44, 16, v39
	s_nop 0
	v_and_b32_e32 v45, 0xffff0000, v39
	s_nop 0
	v_mov_b32_e32 v54, v217
	v_mov_b32_e32 v55, v218
	v_mov_b32_e32 v56, v219
	v_mov_b32_e32 v57, v221
	v_mov_b32_e32 v62, v222
	v_mov_b32_e32 v63, v223
	v_mov_b32_e32 v64, v224
	v_mov_b32_e32 v65, v225
	s_waitcnt vmcnt(0) lgkmcnt(0)
	v_lshlrev_b32_e32 v26, 16, v51
	v_and_b32_e32 v27, 0xffff0000, v51
	s_nop 0
	v_lshlrev_b32_e32 v28, 16, v54
	s_nop 0
	v_and_b32_e32 v29, 0xffff0000, v54
	s_nop 0
	v_lshlrev_b32_e32 v30, 16, v55
	s_nop 0
	v_mov_b32_e32 v77, v226
	v_mov_b32_e32 v81, v227
	v_mov_b32_e32 v152, v228
	v_mov_b32_e32 v153, v229
	v_mov_b32_e32 v154, v230
	v_add_co_u32_e32 v16, vcc, 0xffffec00, v60
	v_lshlrev_b32_e32 v18, 16, v41
	s_nop 0
	v_addc_co_u32_e32 v17, vcc, -1, v61, vcc
	v_mov_b32_e32 v155, v231
	v_lshlrev_b32_e32 v16, 16, v40
	v_and_b32_e32 v17, 0xffff0000, v40
	v_and_b32_e32 v19, 0xffff0000, v41
	v_lshlrev_b32_e32 v20, 16, v42
	v_and_b32_e32 v21, 0xffff0000, v42
	v_lshlrev_b32_e32 v22, 16, v43
	v_and_b32_e32 v23, 0xffff0000, v43
	v_lshlrev_b32_e32 v24, 16, v50
	v_and_b32_e32 v25, 0xffff0000, v50
	v_lshlrev_b32_e32 v42, 16, v52
	v_and_b32_e32 v43, 0xffff0000, v52
	v_lshlrev_b32_e32 v40, 16, v53
	v_and_b32_e32 v41, 0xffff0000, v53
	v_and_b32_e32 v31, 0xffff0000, v55
	v_lshlrev_b32_e32 v32, 16, v56
	v_and_b32_e32 v33, 0xffff0000, v56
	v_lshlrev_b32_e32 v34, 16, v57
	v_and_b32_e32 v35, 0xffff0000, v57
	v_lshlrev_b32_e32 v36, 16, v62
	v_and_b32_e32 v37, 0xffff0000, v62
	v_lshlrev_b32_e32 v38, 16, v63
	v_and_b32_e32 v39, 0xffff0000, v63
	v_lshlrev_b32_e32 v68, 16, v64
	v_and_b32_e32 v69, 0xffff0000, v64
	v_lshlrev_b32_e32 v66, 16, v65
	v_and_b32_e32 v67, 0xffff0000, v65
	s_waitcnt vmcnt(0) lgkmcnt(0)
	v_lshlrev_b32_e32 v50, 16, v77
	v_and_b32_e32 v51, 0xffff0000, v77
	v_lshlrev_b32_e32 v52, 16, v81
	v_and_b32_e32 v53, 0xffff0000, v81
	v_lshlrev_b32_e32 v54, 16, v152
	v_and_b32_e32 v55, 0xffff0000, v152
	v_lshlrev_b32_e32 v56, 16, v153
	v_and_b32_e32 v57, 0xffff0000, v153
	v_lshlrev_b32_e32 v62, 16, v154
	v_and_b32_e32 v63, 0xffff0000, v154
	v_lshlrev_b32_e32 v64, 16, v155
	v_and_b32_e32 v65, 0xffff0000, v155
.LBB0_357:
	s_or_b64 exec, exec, s[2:3]
	s_waitcnt vmcnt(0)
	v_add_co_u32_e32 v152, vcc, s7, v60
	v_mov_b32_e32 v81, v175
	s_nop 0
	v_addc_co_u32_e32 v153, vcc, 0, v61, vcc
	v_add_co_u32_e32 v154, vcc, s8, v60
	s_nop 1
	v_addc_co_u32_e32 v155, vcc, 0, v61, vcc
	v_add_co_u32_e32 v156, vcc, s9, v60
	s_nop 1
	v_addc_co_u32_e32 v157, vcc, 0, v61, vcc
	v_add_co_u32_e32 v158, vcc, s12, v60
	s_nop 1
	v_addc_co_u32_e32 v159, vcc, 0, v61, vcc
	v_add_co_u32_e32 v160, vcc, 0x6000, v60
	s_nop 1
	v_addc_co_u32_e32 v161, vcc, 0, v61, vcc
	v_add_co_u32_e32 v162, vcc, 0x7000, v60
	s_nop 1
	v_addc_co_u32_e32 v163, vcc, 0, v61, vcc
	v_add_co_u32_e32 v164, vcc, 0x8000, v60
	s_nop 1
	v_addc_co_u32_e32 v165, vcc, 0, v61, vcc
	v_mov_b32_e32 v192, v233
	v_mov_b32_e32 v191, v234
	v_mov_b32_e32 v190, v235
	v_mov_b32_e32 v189, v236
	v_mov_b32_e32 v188, v237
	v_mov_b32_e32 v187, v238
	v_mov_b32_e32 v186, v239
	v_mov_b32_e32 v193, v232
	v_mad_i64_i32 v[60:61], s[2:3], v76, s10, 0
	s_mov_b64 s[2:3], 0
	v_lshl_add_u64 v[60:61], v[150:151], 0, v[60:61]
	s_waitcnt vmcnt(0) lgkmcnt(0)
	v_mov_b32_e32 v178, v192
	v_mov_b32_e32 v179, v191
	v_mov_b32_e32 v180, v190
	v_mov_b32_e32 v181, v189
	v_mov_b32_e32 v183, v188
	v_mov_b32_e32 v184, v187
	v_mov_b32_e32 v185, v186
	v_mov_b32_e32 v182, v193
	s_mov_b32 s96, 0
	s_cmp_lg_u32 s13, 0
	s_cbranch_scc1 .Lcv_nopf
	s_cmp_eq_u64 s[50:51], 0
	s_cbranch_scc1 .Lcv_nopf
	s_cmpk_gt_i32 s15, 0x1ff
	s_cbranch_scc1 .Lcv_nopf
; #define LAS __attribute__((address_space(3)))
; #define GLU2(uu) ((f32x2){bflo(uu), bfhi(uu)})
; __global__ void __launch_bounds__(NWAVES * 64, 2) mk_fwd(Args args) {
;     ...
;             for (int kt = 0, tile = (G == 256) ? 64 * (vcu >> 5) + (vcu & 31) : vcu; tile < T / 64; ++kt, tile = (G == 256) ? ((kt < 2) ? 64 * (vcu >> 5) + 32 * kt + (vcu & 31) : T) : tile + G) {
;                 const int R0 = tile * 64, tl0 = R0 % SEQ;
;                 const bf16* zb = Z + (size_t)(R0 + 32 * th) * ZP + 2 * cp;
;                 f32x2 win[38]; unsigned ru[8];
; #pragma unroll
;                 for (int i = 0; i < 38; ++i) win[i] = (f32x2){0.f, 0.f};
;                 if (tl0 + 32 * th > 0) {
; #pragma unroll
;                     for (int i = 0; i < 30; ++i) { const bf16* zr = zb + (long)(i - 30) * ZP; const unsigned uu = *(const unsigned*)zr; win[8 + i] = GLU2(uu); } }
; #pragma unroll
;                 for (int i = 0; i < 8; ++i) { const bf16* zr = zb + (long)i * ZP; ru[i] = *(const unsigned*)zr; }
;     ...
;                     for (int o = 0; o < 8; ++o) { f32x2 y = cb;
; #pragma unroll
;                         for (int j = 0; j < 31; ++j) y += w[j] * win[o + j];
;                         *(LAS f32x2*)(yt + (tb + o) * 512 + 2 * cp) = y; }
	s_mov_b32 s96, 1
	v_add_u32_e32 v246, 0x800, v76
	v_cmp_gt_i32_e32 vcc, s5, v167
	v_mad_i64_i32 v[244:245], s[98:99], v246, s10, v[146:147]
	v_mov_b64_e32 v[242:243], v[244:245]
	global_load_dword v232, v[242:243], off
	v_lshl_add_u64 v[242:243], v[242:243], 0, s[92:93]
	global_load_dword v233, v[242:243], off
	v_lshl_add_u64 v[242:243], v[242:243], 0, s[92:93]
	global_load_dword v234, v[242:243], off
	v_lshl_add_u64 v[242:243], v[242:243], 0, s[92:93]
	global_load_dword v235, v[242:243], off
	v_lshl_add_u64 v[242:243], v[242:243], 0, s[92:93]
	global_load_dword v236, v[242:243], off
	v_lshl_add_u64 v[242:243], v[242:243], 0, s[92:93]
	global_load_dword v237, v[242:243], off
	v_lshl_add_u64 v[242:243], v[242:243], 0, s[92:93]
	global_load_dword v238, v[242:243], off
	v_lshl_add_u64 v[242:243], v[242:243], 0, s[92:93]
	global_load_dword v239, v[242:243], off
	s_and_saveexec_b64 s[98:99], vcc
	v_lshl_add_u64 v[240:241], v[244:245], 0, s[94:95]
	global_load_dword v201, v[240:241], off
	v_lshl_add_u64 v[240:241], v[240:241], 0, s[92:93]
	global_load_dword v202, v[240:241], off
	v_lshl_add_u64 v[240:241], v[240:241], 0, s[92:93]
	global_load_dword v203, v[240:241], off
	v_lshl_add_u64 v[240:241], v[240:241], 0, s[92:93]
	global_load_dword v204, v[240:241], off
	v_lshl_add_u64 v[240:241], v[240:241], 0, s[92:93]
	global_load_dword v205, v[240:241], off
	v_lshl_add_u64 v[240:241], v[240:241], 0, s[92:93]
	global_load_dword v206, v[240:241], off
	v_lshl_add_u64 v[240:241], v[240:241], 0, s[92:93]
	global_load_dword v207, v[240:241], off
	v_lshl_add_u64 v[240:241], v[240:241], 0, s[92:93]
	global_load_dword v208, v[240:241], off
	v_lshl_add_u64 v[240:241], v[240:241], 0, s[92:93]
	global_load_dword v209, v[240:241], off
	v_lshl_add_u64 v[240:241], v[240:241], 0, s[92:93]
	global_load_dword v210, v[240:241], off
	v_lshl_add_u64 v[240:241], v[240:241], 0, s[92:93]
	global_load_dword v211, v[240:241], off
	v_lshl_add_u64 v[240:241], v[240:241], 0, s[92:93]
	global_load_dword v212, v[240:241], off
	v_lshl_add_u64 v[240:241], v[240:241], 0, s[92:93]
	global_load_dword v213, v[240:241], off
	v_lshl_add_u64 v[240:241], v[240:241], 0, s[92:93]
	global_load_dword v214, v[240:241], off
	v_lshl_add_u64 v[240:241], v[240:241], 0, s[92:93]
	global_load_dword v215, v[240:241], off
	v_lshl_add_u64 v[240:241], v[240:241], 0, s[92:93]
	global_load_dword v216, v[240:241], off
	v_lshl_add_u64 v[240:241], v[240:241], 0, s[92:93]
	global_load_dword v217, v[240:241], off
	v_lshl_add_u64 v[240:241], v[240:241], 0, s[92:93]
	global_load_dword v218, v[240:241], off
	v_lshl_add_u64 v[240:241], v[240:241], 0, s[92:93]
	global_load_dword v219, v[240:241], off
	v_lshl_add_u64 v[240:241], v[240:241], 0, s[92:93]
	global_load_dword v221, v[240:241], off
	v_lshl_add_u64 v[240:241], v[240:241], 0, s[92:93]
	global_load_dword v222, v[240:241], off
	v_lshl_add_u64 v[240:241], v[240:241], 0, s[92:93]
	global_load_dword v223, v[240:241], off
	v_lshl_add_u64 v[240:241], v[240:241], 0, s[92:93]
	global_load_dword v224, v[240:241], off
	v_lshl_add_u64 v[240:241], v[240:241], 0, s[92:93]
	global_load_dword v225, v[240:241], off
	v_lshl_add_u64 v[240:241], v[240:241], 0, s[92:93]
	global_load_dword v226, v[240:241], off
	v_lshl_add_u64 v[240:241], v[240:241], 0, s[92:93]
	global_load_dword v227, v[240:241], off
	v_lshl_add_u64 v[240:241], v[240:241], 0, s[92:93]
	global_load_dword v228, v[240:241], off
	v_lshl_add_u64 v[240:241], v[240:241], 0, s[92:93]
	global_load_dword v229, v[240:241], off
	v_lshl_add_u64 v[240:241], v[240:241], 0, s[92:93]
	global_load_dword v230, v[240:241], off
	v_lshl_add_u64 v[240:241], v[240:241], 0, s[92:93]
	global_load_dword v231, v[240:241], off
	s_or_b64 exec, exec, s[98:99]
.Lcv_nopf:
	s_branch .LBB0_359
.LBB0_358:
	v_pk_fma_f32 v[78:79], v[82:83], v[78:79], v[144:145]
	v_lshlrev_b32_e32 v68, 16, v193
	v_pk_fma_f32 v[78:79], v[84:85], v[74:75], v[78:79]
	v_pk_fma_f32 v[74:75], v[82:83], v[74:75], v[144:145]
	v_pk_fma_f32 v[78:79], v[86:87], v[72:73], v[78:79]
	v_pk_fma_f32 v[74:75], v[84:85], v[72:73], v[74:75]
	v_pk_fma_f32 v[72:73], v[82:83], v[72:73], v[144:145]
	v_pk_fma_f32 v[78:79], v[88:89], v[70:71], v[78:79]
	v_pk_fma_f32 v[74:75], v[86:87], v[70:71], v[74:75]
	v_pk_fma_f32 v[72:73], v[84:85], v[70:71], v[72:73]
	v_pk_fma_f32 v[70:71], v[82:83], v[70:71], v[144:145]
	v_pk_fma_f32 v[78:79], v[90:91], v[58:59], v[78:79]
	v_pk_fma_f32 v[74:75], v[88:89], v[58:59], v[74:75]
	v_pk_fma_f32 v[72:73], v[86:87], v[58:59], v[72:73]
	v_pk_fma_f32 v[70:71], v[84:85], v[58:59], v[70:71]
	v_pk_fma_f32 v[58:59], v[82:83], v[58:59], v[144:145]
	v_pk_fma_f32 v[78:79], v[92:93], v[46:47], v[78:79]
	v_pk_fma_f32 v[74:75], v[90:91], v[46:47], v[74:75]
	v_pk_fma_f32 v[72:73], v[88:89], v[46:47], v[72:73]
	v_pk_fma_f32 v[70:71], v[86:87], v[46:47], v[70:71]
	v_pk_fma_f32 v[58:59], v[84:85], v[46:47], v[58:59]
	v_pk_fma_f32 v[46:47], v[82:83], v[46:47], v[144:145]
	v_pk_fma_f32 v[58:59], v[86:87], v[48:49], v[58:59]
	v_pk_fma_f32 v[46:47], v[84:85], v[48:49], v[46:47]
	v_pk_fma_f32 v[58:59], v[88:89], v[44:45], v[58:59]
	v_pk_fma_f32 v[46:47], v[86:87], v[44:45], v[46:47]
	v_pk_fma_f32 v[58:59], v[90:91], v[154:155], v[58:59]
	v_pk_fma_f32 v[46:47], v[88:89], v[154:155], v[46:47]
	v_pk_fma_f32 v[58:59], v[92:93], v[156:157], v[58:59]
	v_pk_fma_f32 v[46:47], v[90:91], v[156:157], v[46:47]
	v_pk_fma_f32 v[58:59], v[94:95], v[158:159], v[58:59]
	v_pk_fma_f32 v[46:47], v[92:93], v[158:159], v[46:47]
	v_pk_fma_f32 v[58:59], v[96:97], v[160:161], v[58:59]
	v_pk_fma_f32 v[46:47], v[94:95], v[160:161], v[46:47]
	v_pk_fma_f32 v[58:59], v[98:99], v[162:163], v[58:59]
; #define LAS __attribute__((address_space(3)))
; #define GLU2(uu) ((f32x2){bflo(uu), bfhi(uu)})
; __global__ void __launch_bounds__(NWAVES * 64, 2) mk_fwd(Args args) {
;     ...
;                 for (int blk = 0; blk < 4; ++blk) {
;                     const int tb = 32 * th + 8 * blk;
; #pragma unroll
;                     for (int i = 0; i < 30; ++i) win[i] = win[i + 8];
; #pragma unroll
;                     for (int i = 0; i < 8; ++i) win[30 + i] = GLU2(ru[i]);
;                     if (blk < 3) {
; #pragma unroll
;                         for (int i = 0; i < 8; ++i) { const bf16* zr = zb + (long)(8 * blk + 8 + i) * ZP; ru[i] = *(const unsigned*)zr; } }
; #pragma unroll
;                     for (int o = 0; o < 8; ++o) { f32x2 y = cb;
; #pragma unroll
;                         for (int j = 0; j < 31; ++j) y += w[j] * win[o + j];
;                         *(LAS f32x2*)(yt + (tb + o) * 512 + 2 * cp) = y; }
	v_pk_fma_f32 v[46:47], v[96:97], v[162:163], v[46:47]
	v_pk_fma_f32 v[58:59], v[100:101], v[164:165], v[58:59]
	v_pk_fma_f32 v[46:47], v[98:99], v[164:165], v[46:47]
	v_pk_fma_f32 v[58:59], v[102:103], v[76:77], v[58:59]
	v_pk_fma_f32 v[46:47], v[100:101], v[76:77], v[46:47]
	v_pk_fma_f32 v[58:59], v[104:105], v[152:153], v[58:59]
	v_pk_fma_f32 v[46:47], v[102:103], v[152:153], v[46:47]
	v_pk_fma_f32 v[58:59], v[106:107], v[16:17], v[58:59]
	v_pk_fma_f32 v[46:47], v[104:105], v[16:17], v[46:47]
	v_pk_fma_f32 v[58:59], v[108:109], v[18:19], v[58:59]
	v_pk_fma_f32 v[46:47], v[106:107], v[18:19], v[46:47]
	v_pk_fma_f32 v[58:59], v[110:111], v[20:21], v[58:59]
	v_pk_fma_f32 v[46:47], v[108:109], v[20:21], v[46:47]
	v_pk_fma_f32 v[58:59], v[112:113], v[22:23], v[58:59]
	v_pk_fma_f32 v[46:47], v[110:111], v[22:23], v[46:47]
	v_pk_fma_f32 v[58:59], v[114:115], v[24:25], v[58:59]
	v_pk_fma_f32 v[46:47], v[112:113], v[24:25], v[46:47]
	v_pk_fma_f32 v[58:59], v[116:117], v[26:27], v[58:59]
	v_pk_fma_f32 v[46:47], v[114:115], v[26:27], v[46:47]
	v_pk_fma_f32 v[58:59], v[118:119], v[42:43], v[58:59]
	v_pk_fma_f32 v[46:47], v[116:117], v[42:43], v[46:47]
	v_pk_fma_f32 v[58:59], v[120:121], v[40:41], v[58:59]
	v_pk_fma_f32 v[46:47], v[118:119], v[40:41], v[46:47]
	v_pk_fma_f32 v[58:59], v[122:123], v[28:29], v[58:59]
	v_pk_fma_f32 v[46:47], v[120:121], v[28:29], v[46:47]
	v_pk_fma_f32 v[58:59], v[124:125], v[30:31], v[58:59]
	v_pk_fma_f32 v[46:47], v[122:123], v[30:31], v[46:47]
	v_pk_fma_f32 v[58:59], v[126:127], v[32:33], v[58:59]
	v_pk_fma_f32 v[46:47], v[124:125], v[32:33], v[46:47]
	v_pk_fma_f32 v[58:59], v[128:129], v[34:35], v[58:59]
	v_pk_fma_f32 v[46:47], v[126:127], v[34:35], v[46:47]
	v_and_b32_e32 v69, 0xffff0000, v193
	v_pk_fma_f32 v[46:47], v[128:129], v[36:37], v[46:47]
	v_pk_fma_f32 v[58:59], v[130:131], v[36:37], v[58:59]
	v_pk_fma_f32 v[46:47], v[130:131], v[38:39], v[46:47]
	v_lshlrev_b32_e32 v66, 16, v192
	v_and_b32_e32 v67, 0xffff0000, v192
	v_pk_fma_f32 v[58:59], v[132:133], v[38:39], v[58:59]
	v_pk_fma_f32 v[46:47], v[132:133], v[68:69], v[46:47]
	v_lshlrev_b32_e32 v50, 16, v191
	v_and_b32_e32 v51, 0xffff0000, v191
	v_pk_fma_f32 v[58:59], v[134:135], v[68:69], v[58:59]
	v_pk_fma_f32 v[46:47], v[134:135], v[66:67], v[46:47]
	v_lshlrev_b32_e32 v52, 16, v190
	v_and_b32_e32 v53, 0xffff0000, v190
	v_pk_fma_f32 v[58:59], v[136:137], v[66:67], v[58:59]
	v_pk_fma_f32 v[46:47], v[136:137], v[50:51], v[46:47]
	v_lshlrev_b32_e32 v54, 16, v189
	v_and_b32_e32 v55, 0xffff0000, v189
	v_pk_fma_f32 v[58:59], v[138:139], v[50:51], v[58:59]
	v_pk_fma_f32 v[46:47], v[138:139], v[52:53], v[46:47]
	v_lshlrev_b32_e32 v56, 16, v188
	v_and_b32_e32 v57, 0xffff0000, v188
	v_pk_fma_f32 v[58:59], v[140:141], v[52:53], v[58:59]
	v_pk_fma_f32 v[46:47], v[140:141], v[54:55], v[46:47]
	v_pk_fma_f32 v[58:59], v[142:143], v[54:55], v[58:59]
	v_pk_fma_f32 v[46:47], v[142:143], v[56:57], v[46:47]
	v_pk_fma_f32 v[78:79], v[94:95], v[48:49], v[78:79]
	v_pk_fma_f32 v[74:75], v[92:93], v[48:49], v[74:75]
	v_pk_fma_f32 v[72:73], v[90:91], v[48:49], v[72:73]
	v_pk_fma_f32 v[70:71], v[88:89], v[48:49], v[70:71]
	ds_write2st64_b64 v81, v[58:59], v[46:47] offset0:16 offset1:20
	v_pk_fma_f32 v[46:47], v[82:83], v[48:49], v[144:145]
	v_pk_fma_f32 v[78:79], v[96:97], v[44:45], v[78:79]
	v_pk_fma_f32 v[74:75], v[94:95], v[44:45], v[74:75]
	v_pk_fma_f32 v[72:73], v[92:93], v[44:45], v[72:73]
	v_pk_fma_f32 v[70:71], v[90:91], v[44:45], v[70:71]
	v_pk_fma_f32 v[46:47], v[84:85], v[44:45], v[46:47]
	v_pk_fma_f32 v[44:45], v[82:83], v[44:45], v[144:145]
	v_pk_fma_f32 v[46:47], v[86:87], v[154:155], v[46:47]
	v_pk_fma_f32 v[44:45], v[84:85], v[154:155], v[44:45]
	v_pk_fma_f32 v[46:47], v[88:89], v[156:157], v[46:47]
	v_pk_fma_f32 v[44:45], v[86:87], v[156:157], v[44:45]
	v_pk_fma_f32 v[46:47], v[90:91], v[158:159], v[46:47]
	v_pk_fma_f32 v[44:45], v[88:89], v[158:159], v[44:45]
	v_pk_fma_f32 v[70:71], v[92:93], v[154:155], v[70:71]
	v_pk_fma_f32 v[44:45], v[90:91], v[160:161], v[44:45]
	v_pk_fma_f32 v[46:47], v[92:93], v[160:161], v[46:47]
	v_pk_fma_f32 v[44:45], v[92:93], v[162:163], v[44:45]
	v_pk_fma_f32 v[72:73], v[94:95], v[154:155], v[72:73]
	v_pk_fma_f32 v[70:71], v[94:95], v[156:157], v[70:71]
	v_pk_fma_f32 v[46:47], v[94:95], v[162:163], v[46:47]
	v_pk_fma_f32 v[44:45], v[94:95], v[164:165], v[44:45]
	v_pk_fma_f32 v[74:75], v[96:97], v[154:155], v[74:75]
	v_pk_fma_f32 v[72:73], v[96:97], v[156:157], v[72:73]
	v_pk_fma_f32 v[70:71], v[96:97], v[158:159], v[70:71]
	v_pk_fma_f32 v[46:47], v[96:97], v[164:165], v[46:47]
	v_pk_fma_f32 v[44:45], v[96:97], v[76:77], v[44:45]
	v_pk_fma_f32 v[78:79], v[98:99], v[154:155], v[78:79]
	v_pk_fma_f32 v[74:75], v[98:99], v[156:157], v[74:75]
	v_pk_fma_f32 v[72:73], v[98:99], v[158:159], v[72:73]
	v_pk_fma_f32 v[70:71], v[98:99], v[160:161], v[70:71]
	v_pk_fma_f32 v[46:47], v[98:99], v[76:77], v[46:47]
	v_pk_fma_f32 v[44:45], v[98:99], v[152:153], v[44:45]
	v_pk_fma_f32 v[78:79], v[100:101], v[156:157], v[78:79]
	v_pk_fma_f32 v[74:75], v[100:101], v[158:159], v[74:75]
	v_pk_fma_f32 v[72:73], v[100:101], v[160:161], v[72:73]
	v_pk_fma_f32 v[70:71], v[100:101], v[162:163], v[70:71]
	v_pk_fma_f32 v[46:47], v[100:101], v[152:153], v[46:47]
	v_pk_fma_f32 v[44:45], v[100:101], v[16:17], v[44:45]
	v_pk_fma_f32 v[78:79], v[102:103], v[158:159], v[78:79]
	v_pk_fma_f32 v[74:75], v[102:103], v[160:161], v[74:75]
	v_pk_fma_f32 v[72:73], v[102:103], v[162:163], v[72:73]
	v_pk_fma_f32 v[70:71], v[102:103], v[164:165], v[70:71]
	v_pk_fma_f32 v[46:47], v[102:103], v[16:17], v[46:47]
	v_pk_fma_f32 v[44:45], v[102:103], v[18:19], v[44:45]
; #define LAS __attribute__((address_space(3)))
; __global__ void __launch_bounds__(NWAVES * 64, 2) mk_fwd(Args args) {
;     ...
;                     for (int o = 0; o < 8; ++o) { f32x2 y = cb;
; #pragma unroll
;                         for (int j = 0; j < 31; ++j) y += w[j] * win[o + j];
;                         *(LAS f32x2*)(yt + (tb + o) * 512 + 2 * cp) = y; }
	v_pk_fma_f32 v[78:79], v[104:105], v[160:161], v[78:79]
	v_pk_fma_f32 v[74:75], v[104:105], v[162:163], v[74:75]
	v_pk_fma_f32 v[72:73], v[104:105], v[164:165], v[72:73]
	v_pk_fma_f32 v[70:71], v[104:105], v[76:77], v[70:71]
	v_pk_fma_f32 v[46:47], v[104:105], v[18:19], v[46:47]
	v_pk_fma_f32 v[44:45], v[104:105], v[20:21], v[44:45]
	v_pk_fma_f32 v[78:79], v[106:107], v[162:163], v[78:79]
	v_pk_fma_f32 v[74:75], v[106:107], v[164:165], v[74:75]
	v_pk_fma_f32 v[72:73], v[106:107], v[76:77], v[72:73]
	v_pk_fma_f32 v[70:71], v[106:107], v[152:153], v[70:71]
	v_pk_fma_f32 v[46:47], v[106:107], v[20:21], v[46:47]
	v_pk_fma_f32 v[44:45], v[106:107], v[22:23], v[44:45]
	v_pk_fma_f32 v[78:79], v[108:109], v[164:165], v[78:79]
	v_pk_fma_f32 v[74:75], v[108:109], v[76:77], v[74:75]
	v_pk_fma_f32 v[72:73], v[108:109], v[152:153], v[72:73]
	v_pk_fma_f32 v[70:71], v[108:109], v[16:17], v[70:71]
	v_pk_fma_f32 v[46:47], v[108:109], v[22:23], v[46:47]
	v_pk_fma_f32 v[44:45], v[108:109], v[24:25], v[44:45]
	v_pk_fma_f32 v[78:79], v[110:111], v[76:77], v[78:79]
	v_pk_fma_f32 v[74:75], v[110:111], v[152:153], v[74:75]
	v_pk_fma_f32 v[72:73], v[110:111], v[16:17], v[72:73]
	v_pk_fma_f32 v[70:71], v[110:111], v[18:19], v[70:71]
	v_pk_fma_f32 v[46:47], v[110:111], v[24:25], v[46:47]
	v_pk_fma_f32 v[44:45], v[110:111], v[26:27], v[44:45]
	v_pk_fma_f32 v[78:79], v[112:113], v[152:153], v[78:79]
	v_pk_fma_f32 v[74:75], v[112:113], v[16:17], v[74:75]
	v_pk_fma_f32 v[72:73], v[112:113], v[18:19], v[72:73]
	v_pk_fma_f32 v[70:71], v[112:113], v[20:21], v[70:71]
	v_pk_fma_f32 v[46:47], v[112:113], v[26:27], v[46:47]
	v_pk_fma_f32 v[44:45], v[112:113], v[42:43], v[44:45]
	v_pk_fma_f32 v[78:79], v[114:115], v[16:17], v[78:79]
	v_pk_fma_f32 v[74:75], v[114:115], v[18:19], v[74:75]
	v_pk_fma_f32 v[72:73], v[114:115], v[20:21], v[72:73]
	v_pk_fma_f32 v[70:71], v[114:115], v[22:23], v[70:71]
	v_pk_fma_f32 v[46:47], v[114:115], v[42:43], v[46:47]
	v_pk_fma_f32 v[44:45], v[114:115], v[40:41], v[44:45]
	v_pk_fma_f32 v[78:79], v[116:117], v[18:19], v[78:79]
	v_pk_fma_f32 v[74:75], v[116:117], v[20:21], v[74:75]
	v_pk_fma_f32 v[72:73], v[116:117], v[22:23], v[72:73]
	v_pk_fma_f32 v[70:71], v[116:117], v[24:25], v[70:71]
	v_pk_fma_f32 v[46:47], v[116:117], v[40:41], v[46:47]
	v_pk_fma_f32 v[44:45], v[116:117], v[28:29], v[44:45]
	v_pk_fma_f32 v[78:79], v[118:119], v[20:21], v[78:79]
	v_pk_fma_f32 v[74:75], v[118:119], v[22:23], v[74:75]
	v_pk_fma_f32 v[72:73], v[118:119], v[24:25], v[72:73]
	v_pk_fma_f32 v[70:71], v[118:119], v[26:27], v[70:71]
	v_pk_fma_f32 v[46:47], v[118:119], v[28:29], v[46:47]
	v_pk_fma_f32 v[44:45], v[118:119], v[30:31], v[44:45]
	v_pk_fma_f32 v[78:79], v[120:121], v[22:23], v[78:79]
	v_pk_fma_f32 v[74:75], v[120:121], v[24:25], v[74:75]
	v_pk_fma_f32 v[72:73], v[120:121], v[26:27], v[72:73]
	v_pk_fma_f32 v[70:71], v[120:121], v[42:43], v[70:71]
	v_pk_fma_f32 v[46:47], v[120:121], v[30:31], v[46:47]
	v_pk_fma_f32 v[44:45], v[120:121], v[32:33], v[44:45]
	v_pk_fma_f32 v[78:79], v[122:123], v[24:25], v[78:79]
	v_pk_fma_f32 v[74:75], v[122:123], v[26:27], v[74:75]
	v_pk_fma_f32 v[72:73], v[122:123], v[42:43], v[72:73]
	v_pk_fma_f32 v[70:71], v[122:123], v[40:41], v[70:71]
	v_pk_fma_f32 v[46:47], v[122:123], v[32:33], v[46:47]
	v_pk_fma_f32 v[44:45], v[122:123], v[34:35], v[44:45]
	v_pk_fma_f32 v[78:79], v[124:125], v[26:27], v[78:79]
	v_pk_fma_f32 v[74:75], v[124:125], v[42:43], v[74:75]
	v_pk_fma_f32 v[72:73], v[124:125], v[40:41], v[72:73]
	v_pk_fma_f32 v[70:71], v[124:125], v[28:29], v[70:71]
	v_pk_fma_f32 v[46:47], v[124:125], v[34:35], v[46:47]
	v_pk_fma_f32 v[44:45], v[124:125], v[36:37], v[44:45]
	v_pk_fma_f32 v[78:79], v[126:127], v[42:43], v[78:79]
	v_pk_fma_f32 v[74:75], v[126:127], v[40:41], v[74:75]
	v_pk_fma_f32 v[72:73], v[126:127], v[28:29], v[72:73]
; #define LAS __attribute__((address_space(3)))
; #define GLU2(uu) ((f32x2){bflo(uu), bfhi(uu)})
; __global__ void __launch_bounds__(NWAVES * 64, 2) mk_fwd(Args args) {
;     ...
;                 for (int blk = 0; blk < 4; ++blk) {
;                     const int tb = 32 * th + 8 * blk;
; #pragma unroll
;                     for (int i = 0; i < 30; ++i) win[i] = win[i + 8];
; #pragma unroll
;                     for (int i = 0; i < 8; ++i) win[30 + i] = GLU2(ru[i]);
;                     if (blk < 3) {
; #pragma unroll
;                         for (int i = 0; i < 8; ++i) { const bf16* zr = zb + (long)(8 * blk + 8 + i) * ZP; ru[i] = *(const unsigned*)zr; } }
; #pragma unroll
;                     for (int o = 0; o < 8; ++o) { f32x2 y = cb;
; #pragma unroll
;                         for (int j = 0; j < 31; ++j) y += w[j] * win[o + j];
;                         *(LAS f32x2*)(yt + (tb + o) * 512 + 2 * cp) = y; }
;                 }
	v_pk_fma_f32 v[70:71], v[126:127], v[30:31], v[70:71]
	v_pk_fma_f32 v[46:47], v[126:127], v[36:37], v[46:47]
	v_pk_fma_f32 v[44:45], v[126:127], v[38:39], v[44:45]
	v_pk_fma_f32 v[78:79], v[128:129], v[40:41], v[78:79]
	v_pk_fma_f32 v[74:75], v[128:129], v[28:29], v[74:75]
	v_pk_fma_f32 v[72:73], v[128:129], v[30:31], v[72:73]
	v_pk_fma_f32 v[70:71], v[128:129], v[32:33], v[70:71]
	v_pk_fma_f32 v[46:47], v[128:129], v[38:39], v[46:47]
	v_pk_fma_f32 v[44:45], v[128:129], v[68:69], v[44:45]
	v_pk_fma_f32 v[78:79], v[130:131], v[28:29], v[78:79]
	v_pk_fma_f32 v[74:75], v[130:131], v[30:31], v[74:75]
	v_pk_fma_f32 v[72:73], v[130:131], v[32:33], v[72:73]
	v_pk_fma_f32 v[70:71], v[130:131], v[34:35], v[70:71]
	v_pk_fma_f32 v[46:47], v[130:131], v[68:69], v[46:47]
	v_pk_fma_f32 v[44:45], v[130:131], v[66:67], v[44:45]
	v_pk_fma_f32 v[78:79], v[132:133], v[30:31], v[78:79]
	v_pk_fma_f32 v[74:75], v[132:133], v[32:33], v[74:75]
	v_pk_fma_f32 v[72:73], v[132:133], v[34:35], v[72:73]
	v_pk_fma_f32 v[70:71], v[132:133], v[36:37], v[70:71]
	v_pk_fma_f32 v[46:47], v[132:133], v[66:67], v[46:47]
	v_pk_fma_f32 v[44:45], v[132:133], v[50:51], v[44:45]
	v_pk_fma_f32 v[78:79], v[134:135], v[32:33], v[78:79]
	v_pk_fma_f32 v[74:75], v[134:135], v[34:35], v[74:75]
	v_pk_fma_f32 v[72:73], v[134:135], v[36:37], v[72:73]
	v_pk_fma_f32 v[70:71], v[134:135], v[38:39], v[70:71]
	v_pk_fma_f32 v[46:47], v[134:135], v[50:51], v[46:47]
	v_pk_fma_f32 v[44:45], v[134:135], v[52:53], v[44:45]
	v_pk_fma_f32 v[78:79], v[136:137], v[34:35], v[78:79]
	v_pk_fma_f32 v[74:75], v[136:137], v[36:37], v[74:75]
	v_pk_fma_f32 v[72:73], v[136:137], v[38:39], v[72:73]
	v_pk_fma_f32 v[70:71], v[136:137], v[68:69], v[70:71]
	v_pk_fma_f32 v[46:47], v[136:137], v[52:53], v[46:47]
	v_pk_fma_f32 v[44:45], v[136:137], v[54:55], v[44:45]
	v_lshlrev_b32_e32 v62, 16, v187
	v_and_b32_e32 v63, 0xffff0000, v187
	v_pk_fma_f32 v[78:79], v[138:139], v[36:37], v[78:79]
	v_pk_fma_f32 v[74:75], v[138:139], v[38:39], v[74:75]
	v_pk_fma_f32 v[72:73], v[138:139], v[68:69], v[72:73]
	v_pk_fma_f32 v[70:71], v[138:139], v[66:67], v[70:71]
	v_pk_fma_f32 v[46:47], v[138:139], v[54:55], v[46:47]
	v_pk_fma_f32 v[44:45], v[138:139], v[56:57], v[44:45]
	v_lshlrev_b32_e32 v64, 16, v186
	v_and_b32_e32 v65, 0xffff0000, v186
	v_pk_fma_f32 v[78:79], v[140:141], v[38:39], v[78:79]
	v_pk_fma_f32 v[74:75], v[140:141], v[68:69], v[74:75]
	v_pk_fma_f32 v[72:73], v[140:141], v[66:67], v[72:73]
	v_pk_fma_f32 v[70:71], v[140:141], v[50:51], v[70:71]
	v_pk_fma_f32 v[46:47], v[140:141], v[56:57], v[46:47]
	v_pk_fma_f32 v[44:45], v[140:141], v[62:63], v[44:45]
	s_add_u32 s2, s2, 0xa000
	v_pk_fma_f32 v[78:79], v[142:143], v[68:69], v[78:79]
	v_pk_fma_f32 v[74:75], v[142:143], v[66:67], v[74:75]
	v_pk_fma_f32 v[72:73], v[142:143], v[50:51], v[72:73]
	v_pk_fma_f32 v[70:71], v[142:143], v[52:53], v[70:71]
	v_pk_fma_f32 v[46:47], v[142:143], v[62:63], v[46:47]
	v_pk_fma_f32 v[44:45], v[142:143], v[64:65], v[44:45]
	s_addc_u32 s3, s3, 0
	ds_write2st64_b64 v81, v[78:79], v[74:75] offset1:4
	ds_write2st64_b64 v81, v[72:73], v[70:71] offset0:8 offset1:12
	ds_write2st64_b64 v81, v[46:47], v[44:45] offset0:24 offset1:28
	v_add_u32_e32 v81, 0x4000, v81
	s_cmp_eq_u32 s2, 0x28000
	v_mov_b64_e32 v[46:47], v[164:165]
	v_mov_b64_e32 v[58:59], v[162:163]
	v_mov_b64_e32 v[70:71], v[160:161]
	v_mov_b64_e32 v[72:73], v[158:159]
	v_mov_b64_e32 v[74:75], v[156:157]
	v_mov_b64_e32 v[78:79], v[154:155]
	s_waitcnt vmcnt(0) lgkmcnt(0)
	v_mov_b32_e32 v186, v185
	v_mov_b32_e32 v187, v184
	v_mov_b32_e32 v188, v183
	v_mov_b32_e32 v189, v181
	v_mov_b32_e32 v190, v180
	v_mov_b32_e32 v191, v179
	v_mov_b32_e32 v192, v178
	v_mov_b32_e32 v193, v182
	v_mov_b32_e32 v44, v152
	v_mov_b32_e32 v45, v153
	v_mov_b32_e32 v48, v76
	v_mov_b32_e32 v49, v77
	s_cbranch_scc1 .LBB0_354
